# prologue: in-proj weight transpose items issue all 32 row loads + 32 gain loads before the first wait (was 32 serial round trips); scan solve rescheduled with deeper LDS prefetch
# speedup vs baseline: 1.0641x; 1.0168x over previous
; template <bool MAPPED>
; __device__ __forceinline__ void transpose_item(const float* W, int ldw, const float* gain, bf16_t* WT, LAS float* scr, int kb, int nb, int lane) {
;     ...
;     int rc = n0 + (lane & 31);
;     if (MAPPED) rc = refcol_in(rc);
;     float tv_[32];
; #pragma unroll
;     for (int i = 0; i < 32; ++i) {
;         const int kk = 2 * i + (lane >> 5);
;         float v = 0.f;
;         if (rc >= 0) { v = W[(size_t)(k0 + kk) * ldw + rc]; if (MAPPED) v *= gain[k0 + kk]; }
;         tv_[i] = v;
.LBB0_29:
	s_andn2_saveexec_b64 s[14:15], s[14:15]
	v_add_u32_e32 v2, 0x1000, v7
	s_or_b64 exec, exec, s[14:15]
	v_mov_b64_e32 v[8:9], s[80:81]
	v_mad_i64_i32 v[12:13], s[14:15], v5, s70, v[8:9]
	v_lshlrev_b32_e32 v8, 10, v5
	v_lshlrev_b32_sdwa v6, v34, sext(v6) dst_sel:DWORD dst_unused:UNUSED_PAD src0_sel:DWORD src1_sel:WORD_0
	v_ashrrev_i32_e32 v9, 31, v8
	v_or_b32_e32 v10, v6, v16
	v_lshl_add_u64 v[8:9], v[8:9], 2, s[78:79]
	v_cmp_lt_i32_e32 vcc, -1, v2
	v_lshl_add_u64 v[12:13], v[2:3], 2, v[12:13]
	v_mov_b32_e32 v2, 0
	v_ashrrev_i32_e32 v11, 31, v10
	v_mov_b32_e32 v7, 0
	v_mov_b32_e32 v7, 0
	v_mov_b32_e32 v2, 0
	v_mov_b32_e32 v38, 0
	v_mov_b32_e32 v37, 0
	v_mov_b32_e32 v40, 0
	v_mov_b32_e32 v39, 0
	v_mov_b32_e32 v42, 0
	v_mov_b32_e32 v41, 0
	v_mov_b32_e32 v44, 0
	v_mov_b32_e32 v43, 0
	v_mov_b32_e32 v46, 0
	v_mov_b32_e32 v45, 0
	v_mov_b32_e32 v48, 0
	v_mov_b32_e32 v47, 0
	v_mov_b32_e32 v50, 0
	v_mov_b32_e32 v49, 0
	v_mov_b32_e32 v52, 0
	v_mov_b32_e32 v51, 0
	v_mov_b32_e32 v54, 0
	v_mov_b32_e32 v53, 0
	v_mov_b32_e32 v56, 0
	v_mov_b32_e32 v55, 0
	v_mov_b32_e32 v58, 0
	v_mov_b32_e32 v57, 0
	v_mov_b32_e32 v60, 0
	v_mov_b32_e32 v59, 0
	v_mov_b32_e32 v62, 0
	v_mov_b32_e32 v61, 0
	v_mov_b32_e32 v64, 0
	v_mov_b32_e32 v63, 0
	v_mov_b32_e32 v66, 0
	v_mov_b32_e32 v65, 0
	s_and_saveexec_b64 s[14:15], vcc
	s_cbranch_execz .LBB0_6
; template <bool MAPPED>
; __device__ __forceinline__ void transpose_item(const float* W, int ldw, const float* gain, bf16_t* WT, LAS float* scr, int kb, int nb, int lane) {
;     ...
; #pragma unroll
;     for (int i = 0; i < 32; ++i) {
;         const int kk = 2 * i + (lane >> 5);
;         float v = 0.f;
;         if (rc >= 0) { v = W[(size_t)(k0 + kk) * ldw + rc]; if (MAPPED) v *= gain[k0 + kk]; }
;         tv_[i] = v;
	v_subrev_u32_e32 v86, s80, v12
	v_mul_u32_u24_e32 v87, 0x8120, v10
	v_lshl_add_u64 v[88:89], v[10:11], 2, v[8:9]
	v_add_u32_e32 v86, v86, v87
	s_mov_b64 s[16:17], s[80:81]
	global_load_dword v90, v86, s[16:17]
	s_add_u32 s16, s16, 0x10240
	s_addc_u32 s17, s17, 0
	global_load_dword v91, v86, s[16:17]
	s_add_u32 s16, s16, 0x10240
	s_addc_u32 s17, s17, 0
	global_load_dword v92, v86, s[16:17]
	s_add_u32 s16, s16, 0x10240
	s_addc_u32 s17, s17, 0
	global_load_dword v93, v86, s[16:17]
	s_add_u32 s16, s16, 0x10240
	s_addc_u32 s17, s17, 0
	global_load_dword v94, v86, s[16:17]
	s_add_u32 s16, s16, 0x10240
	s_addc_u32 s17, s17, 0
	global_load_dword v95, v86, s[16:17]
	s_add_u32 s16, s16, 0x10240
	s_addc_u32 s17, s17, 0
	global_load_dword v96, v86, s[16:17]
	s_add_u32 s16, s16, 0x10240
	s_addc_u32 s17, s17, 0
	global_load_dword v97, v86, s[16:17]
	s_add_u32 s16, s16, 0x10240
	s_addc_u32 s17, s17, 0
	global_load_dword v98, v86, s[16:17]
	s_add_u32 s16, s16, 0x10240
	s_addc_u32 s17, s17, 0
	global_load_dword v99, v86, s[16:17]
	s_add_u32 s16, s16, 0x10240
	s_addc_u32 s17, s17, 0
	global_load_dword v100, v86, s[16:17]
	s_add_u32 s16, s16, 0x10240
	s_addc_u32 s17, s17, 0
	global_load_dword v101, v86, s[16:17]
	s_add_u32 s16, s16, 0x10240
	s_addc_u32 s17, s17, 0
	global_load_dword v102, v86, s[16:17]
	s_add_u32 s16, s16, 0x10240
	s_addc_u32 s17, s17, 0
	global_load_dword v103, v86, s[16:17]
	s_add_u32 s16, s16, 0x10240
	s_addc_u32 s17, s17, 0
	global_load_dword v104, v86, s[16:17]
	s_add_u32 s16, s16, 0x10240
	s_addc_u32 s17, s17, 0
	global_load_dword v105, v86, s[16:17]
	s_add_u32 s16, s16, 0x10240
	s_addc_u32 s17, s17, 0
	global_load_dword v106, v86, s[16:17]
	s_add_u32 s16, s16, 0x10240
	s_addc_u32 s17, s17, 0
	global_load_dword v107, v86, s[16:17]
	s_add_u32 s16, s16, 0x10240
	s_addc_u32 s17, s17, 0
	global_load_dword v108, v86, s[16:17]
	s_add_u32 s16, s16, 0x10240
	s_addc_u32 s17, s17, 0
	global_load_dword v109, v86, s[16:17]
	s_add_u32 s16, s16, 0x10240
	s_addc_u32 s17, s17, 0
	global_load_dword v110, v86, s[16:17]
	s_add_u32 s16, s16, 0x10240
	s_addc_u32 s17, s17, 0
	global_load_dword v111, v86, s[16:17]
	s_add_u32 s16, s16, 0x10240
	s_addc_u32 s17, s17, 0
	global_load_dword v112, v86, s[16:17]
	s_add_u32 s16, s16, 0x10240
	s_addc_u32 s17, s17, 0
	global_load_dword v113, v86, s[16:17]
	s_add_u32 s16, s16, 0x10240
	s_addc_u32 s17, s17, 0
	global_load_dword v114, v86, s[16:17]
	s_add_u32 s16, s16, 0x10240
	s_addc_u32 s17, s17, 0
	global_load_dword v115, v86, s[16:17]
	s_add_u32 s16, s16, 0x10240
	s_addc_u32 s17, s17, 0
	global_load_dword v116, v86, s[16:17]
	s_add_u32 s16, s16, 0x10240
	s_addc_u32 s17, s17, 0
	global_load_dword v117, v86, s[16:17]
	s_add_u32 s16, s16, 0x10240
	s_addc_u32 s17, s17, 0
	global_load_dword v118, v86, s[16:17]
	s_add_u32 s16, s16, 0x10240
	s_addc_u32 s17, s17, 0
	global_load_dword v119, v86, s[16:17]
	s_add_u32 s16, s16, 0x10240
	s_addc_u32 s17, s17, 0
	global_load_dword v120, v86, s[16:17]
	s_add_u32 s16, s16, 0x10240
	s_addc_u32 s17, s17, 0
	global_load_dword v121, v86, s[16:17]
	global_load_dword v122, v[88:89], off offset:0
	global_load_dword v123, v[88:89], off offset:8
	global_load_dword v124, v[88:89], off offset:16
	global_load_dword v125, v[88:89], off offset:24
	global_load_dword v126, v[88:89], off offset:32
	global_load_dword v127, v[88:89], off offset:40
	global_load_dword v128, v[88:89], off offset:48
	global_load_dword v129, v[88:89], off offset:56
	global_load_dword v130, v[88:89], off offset:64
	global_load_dword v131, v[88:89], off offset:72
	global_load_dword v132, v[88:89], off offset:80
	global_load_dword v133, v[88:89], off offset:88
	global_load_dword v134, v[88:89], off offset:96
	global_load_dword v135, v[88:89], off offset:104
	global_load_dword v136, v[88:89], off offset:112
	global_load_dword v137, v[88:89], off offset:120
	global_load_dword v138, v[88:89], off offset:128
	global_load_dword v139, v[88:89], off offset:136
	global_load_dword v140, v[88:89], off offset:144
	global_load_dword v141, v[88:89], off offset:152
	global_load_dword v142, v[88:89], off offset:160
	global_load_dword v143, v[88:89], off offset:168
	global_load_dword v144, v[88:89], off offset:176
	global_load_dword v145, v[88:89], off offset:184
	global_load_dword v146, v[88:89], off offset:192
	global_load_dword v147, v[88:89], off offset:200
	global_load_dword v148, v[88:89], off offset:208
	global_load_dword v149, v[88:89], off offset:216
	global_load_dword v150, v[88:89], off offset:224
	global_load_dword v151, v[88:89], off offset:232
	global_load_dword v152, v[88:89], off offset:240
	global_load_dword v153, v[88:89], off offset:248
	s_waitcnt vmcnt(31)
	v_mul_f32_e32 v7, v90, v122
	s_waitcnt vmcnt(30)
	v_mul_f32_e32 v2, v91, v123
	s_waitcnt vmcnt(29)
	v_mul_f32_e32 v38, v92, v124
	s_waitcnt vmcnt(28)
	v_mul_f32_e32 v37, v93, v125
	s_waitcnt vmcnt(27)
	v_mul_f32_e32 v40, v94, v126
	s_waitcnt vmcnt(26)
	v_mul_f32_e32 v39, v95, v127
	s_waitcnt vmcnt(25)
	v_mul_f32_e32 v42, v96, v128
	s_waitcnt vmcnt(24)
	v_mul_f32_e32 v41, v97, v129
	s_waitcnt vmcnt(23)
	v_mul_f32_e32 v44, v98, v130
	s_waitcnt vmcnt(22)
	v_mul_f32_e32 v43, v99, v131
	s_waitcnt vmcnt(21)
	v_mul_f32_e32 v46, v100, v132
	s_waitcnt vmcnt(20)
	v_mul_f32_e32 v45, v101, v133
	s_waitcnt vmcnt(19)
	v_mul_f32_e32 v48, v102, v134
	s_waitcnt vmcnt(18)
	v_mul_f32_e32 v47, v103, v135
	s_waitcnt vmcnt(17)
	v_mul_f32_e32 v50, v104, v136
	s_waitcnt vmcnt(16)
	v_mul_f32_e32 v49, v105, v137
	s_waitcnt vmcnt(15)
	v_mul_f32_e32 v52, v106, v138
	s_waitcnt vmcnt(14)
	v_mul_f32_e32 v51, v107, v139
	s_waitcnt vmcnt(13)
	v_mul_f32_e32 v54, v108, v140
	s_waitcnt vmcnt(12)
	v_mul_f32_e32 v53, v109, v141
	s_waitcnt vmcnt(11)
	v_mul_f32_e32 v56, v110, v142
	s_waitcnt vmcnt(10)
	v_mul_f32_e32 v55, v111, v143
	s_waitcnt vmcnt(9)
	v_mul_f32_e32 v58, v112, v144
	s_waitcnt vmcnt(8)
	v_mul_f32_e32 v57, v113, v145
	s_waitcnt vmcnt(7)
	v_mul_f32_e32 v60, v114, v146
	s_waitcnt vmcnt(6)
	v_mul_f32_e32 v59, v115, v147
	s_waitcnt vmcnt(5)
	v_mul_f32_e32 v62, v116, v148
	s_waitcnt vmcnt(4)
	v_mul_f32_e32 v61, v117, v149
	s_waitcnt vmcnt(3)
	v_mul_f32_e32 v64, v118, v150
	s_waitcnt vmcnt(2)
	v_mul_f32_e32 v63, v119, v151
	s_waitcnt vmcnt(1)
	v_mul_f32_e32 v66, v120, v152
	s_waitcnt vmcnt(0)
	v_mul_f32_e32 v65, v121, v153
	s_branch .LBB0_6

; #define LAS __attribute__((address_space(3)))
; __device__ __forceinline__ unsigned pk2(float lo, float hi) { f32x2 v = {lo, hi}; bf16x2_t b = __builtin_convertvector(v, bf16x2_t); return __builtin_bit_cast(unsigned, b); }
; __device__ __forceinline__ void scan_pass1(const ScanP& sp, int b, int h, int seg, LAS unsigned char* lds) {
;     ...
;                 for (int r = 0; r < 16; ++r) { const int c = crow(r, hh); NT[c * 32 + ln] = (c < ln) ? Z[r] : 0.f; }
;                 {
;                     const bool lowrow = ln < 16;
;                     u32x2 a_, b_;
;                     a_.x = lowrow ? 0u : pk2(-Z[0], -Z[1]); a_.y = lowrow ? 0u : pk2(-Z[2], -Z[3]);
;                     b_.x = lowrow ? 0u : pk2(-Z[4], -Z[5]); b_.y = lowrow ? 0u : pk2(-Z[6], -Z[7]);
;                     *(LAS u32x2*)(lds + O_N21 + (ln * 40 + 4 * hh) * 2) = a_;
;                     *(LAS u32x2*)(lds + O_N21 + (ln * 40 + 8 + 4 * hh) * 2) = b_;
;                 }
;                 asm volatile("s_waitcnt lgkmcnt(0)" ::: "memory");
;                 float Tr[16];
;                 const int tb = ln >> 4, tl = ln & 15;
;                 const LAS float* NTl = NT + tb * (16 * 32 + 16); asm volatile("" : "+v"(NTl));
;                 f32x4 nvc[4], nvn[4];
; #pragma unroll
;                 for (int m = 0; m < 4; ++m) { nvc[m] = (f32x4){0.f, 0.f, 0.f, 0.f}; nvn[m] = nvc[m]; }
; #pragma unroll
;                 for (int cc = 0; cc < 16; ++cc) {
;                     const int cl = 15 - cc;
;                     if (cl >= 1) {
; #pragma unroll
;                         for (int m = 0; m < 4; ++m) if (4 * m + 3 > cl - 1) nvn[m] = *(const LAS f32x4*)(NTl + (cl - 1) * 32 + 4 * m);
;                     }
;                     float s0 = (cl == tl) ? 1.f : 0.f, s1 = 0.f, s2 = 0.f, s3 = 0.f;
; #pragma unroll
;                     for (int m = 0; m < 4; ++m) {
;                         if (4 * m + 3 > cl) {
;                             if (4 * m + 0 > cl) s0 -= Tr[4 * m + 0] * nvc[m][0];
;                             if (4 * m + 1 > cl) s1 -= Tr[4 * m + 1] * nvc[m][1];
;                             if (4 * m + 2 > cl) s2 -= Tr[4 * m + 2] * nvc[m][2];
;                             if (4 * m + 3 > cl) s3 -= Tr[4 * m + 3] * nvc[m][3];
;                         }
;                     }
;                     Tr[cl] = (s0 + s1) + (s2 + s3);
.LBB0_271:
	s_andn2_b64 vcc, exec, s[78:79]
	s_mov_b32 s78, 0x800000
	s_mov_b32 s79, 0x3f317217
	s_mov_b32 s37, 0x7f800000
	s_movk_i32 s38, 0x5ff
	s_mov_b32 s40, 0xbfb8aa3b
	s_cbranch_vccnz .LBB0_283
	v_readlane_b32 s0, v254, 30
	v_cmp_lt_i32_e32 vcc, v2, v189
	s_movk_i32 s22, 0x840
	v_lshl_add_u32 v119, v189, 2, s0
	v_cndmask_b32_e32 v121, 0, v68, vcc
	v_lshl_add_u32 v123, v188, 9, v119
	ds_write_b32 v123, v121
	v_or_b32_e32 v121, 1, v2
	v_cmp_lt_i32_e32 vcc, v121, v189
	v_lshl_add_u32 v121, v121, 7, v119
	v_xor_b32_e32 v68, 0x80000000, v68
	v_cndmask_b32_e32 v123, 0, v69, vcc
	v_cmp_lt_i32_e32 vcc, v117, v189
	ds_write_b32 v121, v123
	v_lshl_add_u32 v117, v117, 7, v119
	v_cndmask_b32_e32 v121, 0, v70, vcc
	v_cmp_lt_i32_e32 vcc, v116, v189
	ds_write_b32 v117, v121
	v_lshl_add_u32 v116, v116, 7, v119
	v_cndmask_b32_e32 v117, 0, v71, vcc
	v_cmp_lt_i32_e32 vcc, v115, v189
	ds_write_b32 v116, v117
	v_lshl_add_u32 v115, v115, 7, v119
	v_cndmask_b32_e32 v116, 0, v72, vcc
	v_cmp_lt_i32_e32 vcc, v113, v189
	ds_write_b32 v115, v116
	v_lshl_add_u32 v113, v113, 7, v119
	v_cndmask_b32_e32 v115, 0, v73, vcc
	v_cmp_lt_i32_e32 vcc, v109, v189
	ds_write_b32 v113, v115
	v_lshl_add_u32 v109, v109, 7, v119
	v_cndmask_b32_e32 v113, 0, v74, vcc
	v_cmp_lt_i32_e32 vcc, v3, v189
	ds_write_b32 v109, v113
	v_lshl_add_u32 v3, v3, 7, v119
	v_cndmask_b32_e32 v109, 0, v75, vcc
	v_cmp_lt_i32_e32 vcc, v111, v189
	ds_write_b32 v3, v109
	v_mov_b32_e32 v118, s0
	v_cndmask_b32_e32 v3, 0, v76, vcc
	v_lshl_add_u32 v76, v111, 7, v119
	v_cmp_lt_i32_e32 vcc, v106, v189
	ds_write_b32 v76, v3
	v_lshl_add_u32 v76, v106, 7, v119
	v_cndmask_b32_e32 v3, 0, v77, vcc
	v_cmp_lt_i32_e32 vcc, v110, v189
	ds_write_b32 v76, v3
	v_lshl_add_u32 v76, v110, 7, v119
	v_cndmask_b32_e32 v3, 0, v78, vcc
	v_cmp_lt_i32_e32 vcc, v104, v189
	ds_write_b32 v76, v3
	v_lshl_add_u32 v76, v104, 7, v119
	v_cndmask_b32_e32 v3, 0, v79, vcc
	v_cmp_lt_i32_e32 vcc, v114, v189
	ds_write_b32 v76, v3
	v_lshl_add_u32 v76, v114, 7, v119
	v_cndmask_b32_e32 v3, 0, v80, vcc
	v_cmp_lt_i32_e32 vcc, v112, v189
	ds_write_b32 v76, v3
	v_lshl_add_u32 v76, v112, 7, v119
	v_cndmask_b32_e32 v3, 0, v81, vcc
	v_cmp_lt_i32_e32 vcc, v107, v189
	ds_write_b32 v76, v3
	v_lshl_add_u32 v76, v107, 7, v119
	v_cndmask_b32_e32 v3, 0, v82, vcc
	v_cmp_lt_i32_e32 vcc, v105, v189
	ds_write_b32 v76, v3
	v_lshl_add_u32 v76, v105, 7, v119
	v_cndmask_b32_e32 v3, 0, v83, vcc
	ds_write_b32 v76, v3
	v_xor_b32_e32 v3, 0x80000000, v69
	v_cvt_pk_bf16_f32 v3, v68, v3
	v_cmp_gt_u32_e64 s[0:1], 16, v189
	v_xor_b32_e32 v69, 0x80000000, v71
	v_xor_b32_e32 v71, 0x80000000, v75
	v_cndmask_b32_e64 v68, v3, 0, s[0:1]
	v_xor_b32_e32 v3, 0x80000000, v70
	v_cvt_pk_bf16_f32 v3, v3, v69
	v_cndmask_b32_e64 v69, v3, 0, s[0:1]
	v_xor_b32_e32 v3, 0x80000000, v72
	v_xor_b32_e32 v70, 0x80000000, v73
	v_cvt_pk_bf16_f32 v3, v3, v70
	v_cndmask_b32_e64 v70, v3, 0, s[0:1]
	v_xor_b32_e32 v3, 0x80000000, v74
	v_mad_u32_u24 v2, v189, 40, v2
	v_cvt_pk_bf16_f32 v3, v3, v71
	v_lshl_add_u32 v2, v2, 1, 0
	v_cndmask_b32_e64 v71, v3, 0, s[0:1]
	v_add_u32_e32 v2, 0x1aa00, v2
	ds_write2_b64 v2, v[68:69], v[70:71] offset1:2
	v_lshrrev_b32_e32 v2, 4, v189
	v_mad_u32_u24 v109, v2, s22, v118
	v_and_b32_e32 v118, 15, v108
	s_waitcnt lgkmcnt(0)
	ds_read_b128 v[104:107], v109 offset:1840
	ds_read_b128 v[110:113], v109 offset:1712
	ds_read_b128 v[114:117], v109 offset:1584
	ds_read_b128 v[150:153], v109 offset:1456
	v_cmp_eq_u32_e64 s[22:23], 15, v118
	s_nop 1
	v_cndmask_b32_e64 v119, 0, 1.0, s[22:23]
	v_mov_b32_e32 v2, v119
	v_cmp_eq_u32_e64 s[22:23], 14, v118
	ds_read_b128 v[154:157], v109 offset:1312
	ds_read_b128 v[206:209], v109 offset:1328
	v_cndmask_b32_e64 v119, 0, 1.0, s[22:23]
	s_waitcnt lgkmcnt(5)
	v_fma_f32 v123, -v2, v107, 0
	v_add_f32_e32 v3, v123, v119
	v_cmp_eq_u32_e64 s[22:23], 13, v118
	ds_read_b128 v[222:225], v109 offset:1184
	ds_read_b128 v[226:229], v109 offset:1200
	s_waitcnt lgkmcnt(6)
	v_fma_f32 v123, -v2, v113, 0
	v_cndmask_b32_e64 v119, 0, 1.0, s[22:23]
	v_add_f32_e32 v119, v123, v119
	v_fma_f32 v121, -v3, v112, 0
	v_add_f32_e32 v71, v121, v119
	v_cmp_eq_u32_e64 s[22:23], 12, v118
	ds_read_b128 v[230:233], v109 offset:1056
	ds_read_b128 v[234:237], v109 offset:1072
	s_waitcnt lgkmcnt(7)
	v_fma_f32 v121, -v3, v116, 0
	v_fma_f32 v123, -v2, v117, 0
	v_cndmask_b32_e64 v119, 0, 1.0, s[22:23]
	v_add_f32_e32 v119, v121, v119
	v_add_f32_e32 v119, v123, v119
	v_fma_f32 v80, -v71, v115, 0
	v_add_f32_e32 v78, v80, v119
	v_cmp_eq_u32_e64 s[22:23], 11, v118
	ds_read_b128 v[238:241], v109 offset:928
	ds_read_b128 v[242:245], v109 offset:944
	s_waitcnt lgkmcnt(8)
	v_fma_f32 v80, -v71, v151, 0
	v_fma_f32 v121, -v3, v152, 0
	v_fma_f32 v123, -v2, v153, 0
	v_cndmask_b32_e64 v119, 0, 1.0, s[22:23]
	v_add_f32_e32 v119, v80, v119
	v_add_f32_e32 v119, v121, v119
	v_add_f32_e32 v119, v123, v119
	v_fma_f32 v75, -v78, v150, 0
	v_add_f32_e32 v77, v75, v119
	v_cmp_eq_u32_e64 s[22:23], 10, v118
	ds_read_b128 v[246:249], v109 offset:784
	ds_read_b128 v[104:107], v109 offset:800
	ds_read_b128 v[110:113], v109 offset:816
	s_waitcnt lgkmcnt(9)
	v_fma_f32 v75, -v78, v206, 0
	v_fma_f32 v80, -v71, v207, 0
	v_fma_f32 v121, -v3, v208, 0
	v_fma_f32 v123, -v2, v209, 0
	v_cndmask_b32_e64 v119, 0, 1.0, s[22:23]
	v_add_f32_e32 v119, v75, v119
	v_add_f32_e32 v119, v80, v119
	v_add_f32_e32 v119, v121, v119
	v_fma_f32 v123, -v77, v157, v123
	v_add_f32_e32 v79, v123, v119
	v_cmp_eq_u32_e64 s[22:23], 9, v118
	ds_read_b128 v[114:117], v109 offset:656
	ds_read_b128 v[150:153], v109 offset:672
	ds_read_b128 v[154:157], v109 offset:688
	s_waitcnt lgkmcnt(10)
; #define LAS __attribute__((address_space(3)))
; __device__ __forceinline__ void scan_pass1(const ScanP& sp, int b, int h, int seg, LAS unsigned char* lds) {
;     ...
;                 for (int cc = 0; cc < 16; ++cc) {
;                     const int cl = 15 - cc;
;                     if (cl >= 1) {
; #pragma unroll
;                         for (int m = 0; m < 4; ++m) if (4 * m + 3 > cl - 1) nvn[m] = *(const LAS f32x4*)(NTl + (cl - 1) * 32 + 4 * m);
;                     }
;                     float s0 = (cl == tl) ? 1.f : 0.f, s1 = 0.f, s2 = 0.f, s3 = 0.f;
; #pragma unroll
;                     for (int m = 0; m < 4; ++m) {
;                         if (4 * m + 3 > cl) {
;                             if (4 * m + 0 > cl) s0 -= Tr[4 * m + 0] * nvc[m][0];
;                             if (4 * m + 1 > cl) s1 -= Tr[4 * m + 1] * nvc[m][1];
;                             if (4 * m + 2 > cl) s2 -= Tr[4 * m + 2] * nvc[m][2];
;                             if (4 * m + 3 > cl) s3 -= Tr[4 * m + 3] * nvc[m][3];
;                         }
;                     }
;                     Tr[cl] = (s0 + s1) + (s2 + s3);
;                     asm volatile("" : "+v"(Tr[cl]) :: "memory");
; #pragma unroll
;                     for (int m = 0; m < 4; ++m) nvc[m] = nvn[m];
;                 }
;                 if (hh == 0) {
	v_fma_f32 v75, -v78, v226, 0
	v_fma_f32 v80, -v71, v227, 0
	v_fma_f32 v121, -v3, v228, 0
	v_fma_f32 v123, -v2, v229, 0
	v_fma_f32 v123, -v77, v225, v123
	v_cndmask_b32_e64 v119, 0, 1.0, s[22:23]
	v_add_f32_e32 v119, v75, v119
	v_add_f32_e32 v119, v80, v119
	v_add_f32_e32 v119, v123, v119
	v_fma_f32 v121, -v79, v224, v121
	v_add_f32_e32 v81, v121, v119
	v_cmp_eq_u32_e64 s[22:23], 8, v118
	ds_read_b128 v[206:209], v109 offset:528
	ds_read_b128 v[222:225], v109 offset:544
	ds_read_b128 v[226:229], v109 offset:560
	s_waitcnt lgkmcnt(11)
	v_fma_f32 v75, -v78, v234, 0
	v_fma_f32 v80, -v71, v235, 0
	v_fma_f32 v121, -v3, v236, 0
	v_fma_f32 v123, -v2, v237, 0
	v_fma_f32 v121, -v79, v232, v121
	v_fma_f32 v123, -v77, v233, v123
	v_cndmask_b32_e64 v119, 0, 1.0, s[22:23]
	v_add_f32_e32 v119, v75, v119
	v_add_f32_e32 v119, v121, v119
	v_add_f32_e32 v119, v123, v119
	v_fma_f32 v80, -v81, v231, v80
	v_add_f32_e32 v82, v80, v119
	v_cmp_eq_u32_e64 s[22:23], 7, v118
	s_waitcnt lgkmcnt(9)
	v_fma_f32 v75, -v78, v242, 0
	v_fma_f32 v80, -v71, v243, 0
	v_fma_f32 v121, -v3, v244, 0
	v_fma_f32 v123, -v2, v245, 0
	v_fma_f32 v80, -v81, v239, v80
	v_fma_f32 v121, -v79, v240, v121
	v_fma_f32 v123, -v77, v241, v123
	v_cndmask_b32_e64 v119, 0, 1.0, s[22:23]
	v_add_f32_e32 v119, v80, v119
	v_add_f32_e32 v119, v121, v119
	v_add_f32_e32 v119, v123, v119
	v_fma_f32 v75, -v82, v238, v75
	v_add_f32_e32 v76, v75, v119
	v_cmp_eq_u32_e64 s[22:23], 6, v118
	ds_read_b128 v[230:233], v109 offset:400
	ds_read_b128 v[234:237], v109 offset:416
	ds_read_b128 v[238:241], v109 offset:432
	s_waitcnt lgkmcnt(9)
	v_fma_f32 v75, -v78, v110, 0
	v_fma_f32 v80, -v71, v111, 0
	v_fma_f32 v121, -v3, v112, 0
	v_fma_f32 v123, -v2, v113, 0
	v_fma_f32 v75, -v82, v104, v75
	v_fma_f32 v80, -v81, v105, v80
	v_fma_f32 v121, -v79, v106, v121
	v_fma_f32 v123, -v77, v107, v123
	v_cndmask_b32_e64 v119, 0, 1.0, s[22:23]
	v_add_f32_e32 v119, v75, v119
	v_add_f32_e32 v119, v80, v119
	v_add_f32_e32 v119, v121, v119
	v_fma_f32 v123, -v76, v249, v123
	v_add_f32_e32 v83, v123, v119
	v_cmp_eq_u32_e64 s[22:23], 5, v118
	ds_read_b128 v[242:245], v109 offset:256
	ds_read_b128 v[246:249], v109 offset:272
	ds_read_b128 v[104:107], v109 offset:288
	ds_read_b128 v[110:113], v109 offset:304
	s_waitcnt lgkmcnt(10)
	v_fma_f32 v75, -v78, v154, 0
	v_fma_f32 v80, -v71, v155, 0
	v_fma_f32 v121, -v3, v156, 0
	v_fma_f32 v123, -v2, v157, 0
	v_fma_f32 v75, -v82, v150, v75
	v_fma_f32 v80, -v81, v151, v80
	v_fma_f32 v121, -v79, v152, v121
	v_fma_f32 v123, -v77, v153, v123
	v_fma_f32 v123, -v76, v117, v123
	v_cndmask_b32_e64 v119, 0, 1.0, s[22:23]
	v_add_f32_e32 v119, v75, v119
	v_add_f32_e32 v119, v80, v119
	v_add_f32_e32 v119, v123, v119
	v_fma_f32 v121, -v83, v116, v121
	v_add_f32_e32 v70, v121, v119
	v_cmp_eq_u32_e64 s[22:23], 4, v118
	s_waitcnt lgkmcnt(7)
	v_fma_f32 v75, -v78, v226, 0
	v_fma_f32 v80, -v71, v227, 0
	v_fma_f32 v121, -v3, v228, 0
	v_fma_f32 v123, -v2, v229, 0
	v_fma_f32 v75, -v82, v222, v75
	v_fma_f32 v80, -v81, v223, v80
	v_fma_f32 v121, -v79, v224, v121
	v_fma_f32 v123, -v77, v225, v123
	v_fma_f32 v121, -v83, v208, v121
	v_fma_f32 v123, -v76, v209, v123
	v_cndmask_b32_e64 v119, 0, 1.0, s[22:23]
	v_add_f32_e32 v119, v75, v119
	v_add_f32_e32 v119, v121, v119
	v_add_f32_e32 v119, v123, v119
	v_fma_f32 v80, -v70, v207, v80
	v_add_f32_e32 v74, v80, v119
	v_cmp_eq_u32_e64 s[22:23], 3, v118
	ds_read_b128 v[114:117], v109 offset:128
	ds_read_b128 v[150:153], v109 offset:144
	ds_read_b128 v[154:157], v109 offset:160
	ds_read_b128 v[206:209], v109 offset:176
	s_waitcnt lgkmcnt(8)
	v_fma_f32 v75, -v78, v238, 0
	v_fma_f32 v80, -v71, v239, 0
	v_fma_f32 v121, -v3, v240, 0
	v_fma_f32 v123, -v2, v241, 0
	v_fma_f32 v75, -v82, v234, v75
	v_fma_f32 v80, -v81, v235, v80
	v_fma_f32 v121, -v79, v236, v121
	v_fma_f32 v123, -v77, v237, v123
	v_fma_f32 v80, -v70, v231, v80
	v_fma_f32 v121, -v83, v232, v121
	v_fma_f32 v123, -v76, v233, v123
	v_cndmask_b32_e64 v119, 0, 1.0, s[22:23]
	v_add_f32_e32 v119, v80, v119
	v_add_f32_e32 v119, v121, v119
	v_add_f32_e32 v119, v123, v119
	v_fma_f32 v75, -v74, v230, v75
	v_add_f32_e32 v69, v75, v119
	v_cmp_eq_u32_e64 s[22:23], 2, v118
	ds_read_b128 v[222:225], v109 offset:0
	ds_read_b128 v[226:229], v109 offset:16
	ds_read_b128 v[230:233], v109 offset:32
	ds_read_b128 v[234:237], v109 offset:48
	s_waitcnt lgkmcnt(8)
	v_fma_f32 v75, -v78, v110, 0
	v_fma_f32 v80, -v71, v111, 0
	v_fma_f32 v121, -v3, v112, 0
	v_fma_f32 v123, -v2, v113, 0
	v_fma_f32 v75, -v82, v104, v75
	v_fma_f32 v80, -v81, v105, v80
	v_fma_f32 v121, -v79, v106, v121
	v_fma_f32 v123, -v77, v107, v123
	v_fma_f32 v75, -v74, v246, v75
	v_fma_f32 v80, -v70, v247, v80
	v_fma_f32 v121, -v83, v248, v121
	v_fma_f32 v123, -v76, v249, v123
	v_cndmask_b32_e64 v119, 0, 1.0, s[22:23]
	v_add_f32_e32 v119, v75, v119
	v_add_f32_e32 v119, v80, v119
	v_add_f32_e32 v119, v121, v119
	v_fma_f32 v123, -v69, v245, v123
	v_add_f32_e32 v73, v123, v119
	v_cmp_eq_u32_e64 s[22:23], 1, v118
	s_waitcnt lgkmcnt(4)
	v_fma_f32 v75, -v78, v206, 0
	v_fma_f32 v80, -v71, v207, 0
	v_fma_f32 v121, -v3, v208, 0
	v_fma_f32 v123, -v2, v209, 0
	v_fma_f32 v75, -v82, v154, v75
	v_fma_f32 v80, -v81, v155, v80
	v_fma_f32 v121, -v79, v156, v121
	v_fma_f32 v123, -v77, v157, v123
	v_fma_f32 v75, -v74, v150, v75
	v_fma_f32 v80, -v70, v151, v80
	v_fma_f32 v121, -v83, v152, v121
	v_fma_f32 v123, -v76, v153, v123
	v_fma_f32 v123, -v69, v117, v123
	v_cndmask_b32_e64 v119, 0, 1.0, s[22:23]
	v_add_f32_e32 v119, v75, v119
	v_add_f32_e32 v119, v80, v119
	v_add_f32_e32 v119, v123, v119
	v_fma_f32 v121, -v73, v116, v121
	v_add_f32_e32 v68, v121, v119
	v_cmp_eq_u32_e64 s[22:23], 0, v118
	s_waitcnt lgkmcnt(0)
	v_fma_f32 v75, -v78, v234, 0
	v_fma_f32 v80, -v71, v235, 0
	v_fma_f32 v121, -v3, v236, 0
	v_fma_f32 v123, -v2, v237, 0
	v_fma_f32 v75, -v82, v230, v75
	v_fma_f32 v80, -v81, v231, v80
	v_fma_f32 v121, -v79, v232, v121
	v_fma_f32 v123, -v77, v233, v123
	v_fma_f32 v75, -v74, v226, v75
	v_fma_f32 v80, -v70, v227, v80
	v_fma_f32 v121, -v83, v228, v121
	v_fma_f32 v123, -v76, v229, v123
	v_fma_f32 v121, -v73, v224, v121
	v_fma_f32 v123, -v69, v225, v123
	v_cndmask_b32_e64 v119, 0, 1.0, s[22:23]
	v_add_f32_e32 v119, v75, v119
	v_add_f32_e32 v119, v121, v119
	v_add_f32_e32 v119, v123, v119
	v_fma_f32 v80, -v68, v223, v80
	v_add_f32_e32 v72, v80, v119
	v_cmp_lt_u32_e32 vcc, 15, v189
	v_cmp_gt_u32_e64 s[22:23], 32, v108
	s_and_saveexec_b64 s[24:25], s[22:23]
	s_cbranch_execz .LBB0_282
; #define LAS __attribute__((address_space(3)))
; __device__ __forceinline__ unsigned pk2(float lo, float hi) { f32x2 v = {lo, hi}; bf16x2_t b = __builtin_convertvector(v, bf16x2_t); return __builtin_bit_cast(unsigned, b); }
; __device__ __forceinline__ void scan_pass1(const ScanP& sp, int b, int h, int seg, LAS unsigned char* lds) {
;     ...
;                 if (hh == 0) {
; #pragma unroll
;                     for (int q = 0; q < 4; ++q) {
;                         const bool mine = (q >> 1) == tb; const int o8 = 8 * (q & 1);
;                         u32x4 o; o.x = mine ? pk2(Tr[o8], Tr[o8 + 1]) : 0u; o.y = mine ? pk2(Tr[o8 + 2], Tr[o8 + 3]) : 0u; o.z = mine ? pk2(Tr[o8 + 4], Tr[o8 + 5]) : 0u; o.w = mine ? pk2(Tr[o8 + 6], Tr[o8 + 7]) : 0u;
;                         *(LAS u32x4*)(lds + O_TM + ln * 80 + 16 * q) = o;
;                     }
;                 }
	v_cvt_pk_bf16_f32 v68, v72, v68
	v_cvt_pk_bf16_f32 v69, v73, v69
	v_cvt_pk_bf16_f32 v70, v74, v70
	v_cndmask_b32_e64 v72, 0, v68, s[0:1]
	v_cndmask_b32_e64 v73, 0, v69, s[0:1]
	v_cndmask_b32_e64 v74, 0, v70, s[0:1]
	s_and_saveexec_b64 s[22:23], vcc
	s_xor_b64 s[22:23], exec, s[22:23]
	v_mov_b32_e32 v75, s93
	v_mov_b64_e32 v[106:107], v[74:75]
	v_mov_b64_e32 v[104:105], v[72:73]
	s_or_saveexec_b64 s[22:23], s[22:23]
	v_mov_b32_e32 v80, 0
	v_cvt_pk_bf16_f32 v75, v83, v76
	v_cvt_pk_bf16_f32 v76, v82, v81
	s_xor_b64 exec, exec, s[22:23]
	v_mov_b32_e32 v70, 0
	v_mov_b64_e32 v[106:107], v[74:75]
	v_cvt_pk_bf16_f32 v80, v82, v81
	v_mov_b32_e32 v69, v70
	v_mov_b32_e32 v68, v70
	v_mov_b64_e32 v[104:105], v[72:73]
	s_or_b64 exec, exec, s[22:23]
	s_movk_i32 s22, 0x50
	v_mad_u32_u24 v72, v189, s22, 0
	v_cvt_pk_bf16_f32 v77, v79, v77
	v_cvt_pk_bf16_f32 v78, v78, v71
	v_cvt_pk_bf16_f32 v79, v3, v2
	v_add_u32_e32 v72, 0x11800, v72
	v_cndmask_b32_e64 v81, 0, v77, s[0:1]
	v_cndmask_b32_e64 v82, 0, v78, s[0:1]
	v_cndmask_b32_e64 v83, 0, v79, s[0:1]
	v_mov_b32_e32 v71, s93
	ds_write_b128 v72, v[104:107]
	ds_write_b128 v72, v[80:83] offset:16
	s_and_saveexec_b64 s[0:1], vcc
	s_xor_b64 s[0:1], exec, s[0:1]
	v_mov_b32_e32 v71, v75
	s_andn2_saveexec_b64 s[0:1], s[0:1]
	v_mov_b32_e32 v79, 0
	v_mov_b32_e32 v78, v79
	v_mov_b32_e32 v77, v79
	v_mov_b32_e32 v76, v79
	s_or_b64 exec, exec, s[0:1]
	v_mul_u32_u24_e32 v2, 0x50, v189
	s_add_i32 s0, 0, 0x11800
	v_add_u32_e32 v2, s0, v2
	ds_write_b128 v2, v[68:71] offset:32
	ds_write_b128 v2, v[76:79] offset:48
